# prep: the 16 L-matrix entries and the 16 decayed q.k entries of a thread computed together instead of 16 exec-masked blocks with one LDS round trip each
# speedup vs baseline: 1.0191x; 1.0030x over previous
; __device__ __forceinline__ void dn_prep_task(const P& p, int task, unsigned char* sm, int tid) {
;     ...
;     {
;         const int r = tid >> 3, c16 = (tid & 7) * 16;
;         const bf16_t* ks = (const bf16_t*)(p.ws + WS_KN) + (size_t)(m0 + r) * 512 + h * 128 + c16;
;         const bf16_t* qs = (const bf16_t*)(p.ws + WS_QN) + (size_t)(m0 + r) * 512 + h * 128 + c16;
;         *(u32x4*)(kn_s + r * 136 + c16) = *(const u32x4*)ks; *(u32x4*)(kn_s + r * 136 + c16 + 8) = *(const u32x4*)(ks + 8);
;         *(u32x4*)(qn_s + r * 136 + c16) = *(const u32x4*)qs; *(u32x4*)(qn_s + r * 136 + c16 + 8) = *(const u32x4*)(qs + 8);
;         const bf16_t* vs = (const bf16_t*)(p.ws + WS_VV) + (size_t)(m0 + r) * 512 + h * 128 + c16;
;         *(u32x4*)(v_s + r * 136 + c16) = *(const u32x4*)vs; *(u32x4*)(v_s + r * 136 + c16 + 8) = *(const u32x4*)(vs + 8);
;     }
;     if (t2 < 64) {
;         const int tok = dir ? 63 - t2 : t2;
;         const float* gb = (const float*)(p.ws + WS_GB) + (size_t)(m0 + tok) * 16;
;         float gv = gb[dir * 4 + h]; const float bv = gb[8 + dir * 4 + h];
; #pragma unroll
;         for (int o = 1; o < 64; o <<= 1) { const float v = __shfl_up(gv, o); if (lane >= o) gv += v; }
;         gc_s[dir * 64 + t2] = gv; be_s[dir * 64 + t2] = bv;
;     }
;     __syncthreads();
;     {
;         const int which = wave >> 2, it = wave & 3, fr = lane & 15, g = lane >> 4;
;         const bf16_t* As = which ? qn_s : kn_s; float* Out = which ? QK : KK;
;         bf16x8 a[4];
; #pragma unroll
;         for (int ks = 0; ks < 4; ++ks) a[ks] = *(const bf16x8*)(As + (it * 16 + fr) * 136 + ks * 32 + g * 8);
; #pragma unroll
;         for (int jt = 0; jt < 4; ++jt) {
;             f32x4 acc = {0.f, 0.f, 0.f, 0.f};
; #pragma unroll
;             for (int ks = 0; ks < 4; ++ks) { const bf16x8 bb = *(const bf16x8*)(kn_s + (jt * 16 + fr) * 136 + ks * 32 + g * 8); acc = mfma16(a[ks], bb, acc); }
; #pragma unroll
;             for (int r = 0; r < 4; ++r) Out[(it * 16 + 4 * g + r) * 65 + jt * 16 + fr] = acc[r];
;         }
;     }
;     __syncthreads();
;     const float* gc = gc_s + dir * 64; const float* be = be_s + dir * 64; float* L = Ls + dir * 4096;
;     const size_t dt = (size_t)task * 2 + dir;
;     {
;         const int cp = t2 >> 2, s0 = (t2 & 3) * 16; const int ctok = dir ? 63 - cp : cp; const float gcc = gc[cp], bec = be[cp];
; #pragma unroll
.Lpl_b:
	s_or_b64 exec, exec, s[82:83]
	s_waitcnt vmcnt(4)
	ds_write_b128 v89, v[38:41]
	ds_write_b128 v89, v[34:37] offset:16
	s_waitcnt vmcnt(2)
	ds_write_b128 v89, v[46:49] offset:17408
	ds_write_b128 v89, v[42:45] offset:17424
	s_waitcnt vmcnt(0)
	ds_write_b128 v90, v[56:59]
	ds_write_b128 v90, v[52:55] offset:16
	s_waitcnt lgkmcnt(0)
	s_barrier
	ds_read_b128 v[2:5], v148
	ds_read_b128 v[26:29], v148 offset:64
	ds_read_b128 v[30:33], v148 offset:128
	ds_read_b128 v[34:37], v148 offset:192
	ds_read_b128 v[38:41], v149
	ds_read_b128 v[42:45], v149 offset:64
	s_waitcnt lgkmcnt(1)
	v_mfma_f32_16x16x32_bf16 v[38:41], v[2:5], v[38:41], 0
	s_waitcnt lgkmcnt(0)
	v_mfma_f32_16x16x32_bf16 v[38:41], v[26:29], v[42:45], v[38:41]
	ds_read_b128 v[42:45], v149 offset:128
	s_waitcnt lgkmcnt(0)
	v_mfma_f32_16x16x32_bf16 v[38:41], v[30:33], v[42:45], v[38:41]
	ds_read_b128 v[42:45], v149 offset:192
	s_waitcnt lgkmcnt(0)
	v_mfma_f32_16x16x32_bf16 v[38:41], v[34:37], v[42:45], v[38:41]
	s_nop 7
	ds_write_b32 v150, v38
	ds_write_b32 v150, v39 offset:260
	ds_write_b32 v150, v40 offset:520
	ds_write_b32 v150, v41 offset:780
	ds_read_b128 v[38:41], v149 offset:4352
	ds_read_b128 v[42:45], v149 offset:4416
	s_waitcnt lgkmcnt(1)
	v_mfma_f32_16x16x32_bf16 v[38:41], v[2:5], v[38:41], 0
	s_waitcnt lgkmcnt(0)
	v_mfma_f32_16x16x32_bf16 v[38:41], v[26:29], v[42:45], v[38:41]
	ds_read_b128 v[42:45], v149 offset:4480
	s_waitcnt lgkmcnt(0)
	v_mfma_f32_16x16x32_bf16 v[38:41], v[30:33], v[42:45], v[38:41]
	ds_read_b128 v[42:45], v149 offset:4544
	s_waitcnt lgkmcnt(0)
	v_mfma_f32_16x16x32_bf16 v[38:41], v[34:37], v[42:45], v[38:41]
	s_nop 7
	ds_write_b32 v150, v38 offset:64
	ds_write_b32 v150, v39 offset:324
	ds_write_b32 v150, v40 offset:584
	ds_write_b32 v150, v41 offset:844
	ds_read_b128 v[38:41], v149 offset:8704
	ds_read_b128 v[42:45], v149 offset:8768
	s_waitcnt lgkmcnt(1)
	v_mfma_f32_16x16x32_bf16 v[38:41], v[2:5], v[38:41], 0
	s_waitcnt lgkmcnt(0)
	v_mfma_f32_16x16x32_bf16 v[38:41], v[26:29], v[42:45], v[38:41]
	ds_read_b128 v[42:45], v149 offset:8832
	s_waitcnt lgkmcnt(0)
	v_mfma_f32_16x16x32_bf16 v[38:41], v[30:33], v[42:45], v[38:41]
	ds_read_b128 v[42:45], v149 offset:8896
	s_waitcnt lgkmcnt(0)
	v_mfma_f32_16x16x32_bf16 v[38:41], v[34:37], v[42:45], v[38:41]
	s_nop 7
	ds_write_b32 v150, v38 offset:128
	ds_write_b32 v150, v39 offset:388
	ds_write_b32 v150, v40 offset:648
	ds_write_b32 v150, v41 offset:908
	ds_read_b128 v[38:41], v149 offset:13056
	s_waitcnt lgkmcnt(0)
	v_mfma_f32_16x16x32_bf16 v[2:5], v[2:5], v[38:41], 0
	ds_read_b128 v[38:41], v149 offset:13120
	s_waitcnt lgkmcnt(0)
	v_mfma_f32_16x16x32_bf16 v[2:5], v[26:29], v[38:41], v[2:5]
	ds_read_b128 v[26:29], v149 offset:13184
	s_waitcnt lgkmcnt(0)
	v_mfma_f32_16x16x32_bf16 v[2:5], v[30:33], v[26:29], v[2:5]
	ds_read_b128 v[26:29], v149 offset:13248
	s_waitcnt lgkmcnt(0)
	v_mfma_f32_16x16x32_bf16 v[2:5], v[34:37], v[26:29], v[2:5]
	s_nop 7
	ds_write_b32 v150, v2 offset:192
	ds_write_b32 v150, v3 offset:452
	ds_write_b32 v150, v4 offset:712
	ds_write_b32 v150, v5 offset:972
	s_waitcnt lgkmcnt(0)
	s_barrier
	ds_read_b32 v2, v121
	ds_read_b32 v3, v122
	ds_read_b128 v[24:27], v123
	ds_read_b128 v[28:31], v123 offset:16
	ds_read_b128 v[32:35], v123 offset:32
	ds_read_b128 v[36:39], v123 offset:48
	ds_read_b32 v40, v95 offset:34816
	ds_read_b32 v41, v97 offset:34816
	ds_read_b32 v42, v98 offset:34816
	ds_read_b32 v43, v99 offset:34816
	ds_read_b32 v44, v100 offset:34816
	ds_read_b32 v45, v101 offset:34816
	ds_read_b32 v46, v102 offset:34816
	ds_read_b32 v47, v103 offset:34816
	ds_read_b32 v48, v104 offset:34816
	ds_read_b32 v49, v105 offset:34816
	ds_read_b32 v50, v106 offset:34816
	ds_read_b32 v51, v107 offset:34816
	ds_read_b32 v52, v108 offset:34816
	ds_read_b32 v53, v109 offset:34816
	ds_read_b32 v54, v110 offset:34816
	ds_read_b32 v55, v111 offset:34816
	v_bfe_u32 v56, v144, 2, 6
	v_and_b32_e32 v57, 3, v144
	v_lshlrev_b32_e32 v57, 4, v57
	v_sub_u32_e32 v56, v56, v57
	s_waitcnt lgkmcnt(0)
	v_sub_f32_e32 v24, v2, v24
	v_sub_f32_e32 v25, v2, v25
	v_sub_f32_e32 v26, v2, v26
	v_sub_f32_e32 v27, v2, v27
	v_sub_f32_e32 v28, v2, v28
	v_sub_f32_e32 v29, v2, v29
	v_sub_f32_e32 v30, v2, v30
	v_sub_f32_e32 v31, v2, v31
	v_sub_f32_e32 v32, v2, v32
	v_sub_f32_e32 v33, v2, v33
	v_sub_f32_e32 v34, v2, v34
	v_sub_f32_e32 v35, v2, v35
	v_sub_f32_e32 v36, v2, v36
	v_sub_f32_e32 v37, v2, v37
	v_sub_f32_e32 v38, v2, v38
	v_sub_f32_e32 v39, v2, v39
	v_mul_f32_e32 v24, 0x3fb8aa3b, v24
	v_mul_f32_e32 v25, 0x3fb8aa3b, v25
	v_mul_f32_e32 v26, 0x3fb8aa3b, v26
	v_mul_f32_e32 v27, 0x3fb8aa3b, v27
	v_mul_f32_e32 v28, 0x3fb8aa3b, v28
	v_mul_f32_e32 v29, 0x3fb8aa3b, v29
	v_mul_f32_e32 v30, 0x3fb8aa3b, v30
	v_mul_f32_e32 v31, 0x3fb8aa3b, v31
	v_mul_f32_e32 v32, 0x3fb8aa3b, v32
	v_mul_f32_e32 v33, 0x3fb8aa3b, v33
	v_mul_f32_e32 v34, 0x3fb8aa3b, v34
	v_mul_f32_e32 v35, 0x3fb8aa3b, v35
	v_mul_f32_e32 v36, 0x3fb8aa3b, v36
	v_mul_f32_e32 v37, 0x3fb8aa3b, v37
	v_mul_f32_e32 v38, 0x3fb8aa3b, v38
	v_mul_f32_e32 v39, 0x3fb8aa3b, v39
	v_exp_f32_e32 v24, v24
	v_exp_f32_e32 v25, v25
	v_exp_f32_e32 v26, v26
	v_exp_f32_e32 v27, v27
	v_exp_f32_e32 v28, v28
	v_exp_f32_e32 v29, v29
	v_exp_f32_e32 v30, v30
	v_exp_f32_e32 v31, v31
	v_exp_f32_e32 v32, v32
	v_exp_f32_e32 v33, v33
	v_exp_f32_e32 v34, v34
	v_exp_f32_e32 v35, v35
	v_exp_f32_e32 v36, v36
	v_exp_f32_e32 v37, v37
	v_exp_f32_e32 v38, v38
	v_exp_f32_e32 v39, v39
	v_mul_f32_e32 v40, v3, v40
	v_mul_f32_e32 v41, v3, v41
	v_mul_f32_e32 v42, v3, v42
	v_mul_f32_e32 v43, v3, v43
	v_mul_f32_e32 v44, v3, v44
	v_mul_f32_e32 v45, v3, v45
	v_mul_f32_e32 v46, v3, v46
	v_mul_f32_e32 v47, v3, v47
; __device__ __forceinline__ void dn_prep_task(const P& p, int task, unsigned char* sm, int tid) {
;     ...
;         const int cp = t2 >> 2, s0 = (t2 & 3) * 16; const int ctok = dir ? 63 - cp : cp; const float gcc = gc[cp], bec = be[cp];
; #pragma unroll
;         for (int i = 0; i < 16; ++i) { const int sp = s0 + i, stok = dir ? 63 - sp : sp; float v = 0.f; if (cp > sp) v = bec * KK[ctok * 65 + stok] * __expf(gcc - gc[sp]); L[cp * 64 + sp] = v; }
;         const int c = t2 >> 2, c_p = dir ? 63 - c : c; const float gq = gc[c_p];
;         float qv[16];
; #pragma unroll
;         for (int i = 0; i < 16; ++i) { const int s = s0 + i, s_p = dir ? 63 - s : s; qv[i] = (c_p >= s_p) ? QK[c * 65 + s] * SCALE_DK * __expf(gq - gc[s_p]) : 0.f; }
	v_mul_f32_e32 v48, v3, v48
	v_mul_f32_e32 v49, v3, v49
	v_mul_f32_e32 v50, v3, v50
	v_mul_f32_e32 v51, v3, v51
	v_mul_f32_e32 v52, v3, v52
	v_mul_f32_e32 v53, v3, v53
	v_mul_f32_e32 v54, v3, v54
	v_mul_f32_e32 v55, v3, v55
	v_mul_f32_e32 v40, v40, v24
	v_mul_f32_e32 v41, v41, v25
	v_mul_f32_e32 v42, v42, v26
	v_mul_f32_e32 v43, v43, v27
	v_mul_f32_e32 v44, v44, v28
	v_mul_f32_e32 v45, v45, v29
	v_mul_f32_e32 v46, v46, v30
	v_mul_f32_e32 v47, v47, v31
	v_mul_f32_e32 v48, v48, v32
	v_mul_f32_e32 v49, v49, v33
	v_mul_f32_e32 v50, v50, v34
	v_mul_f32_e32 v51, v51, v35
	v_mul_f32_e32 v52, v52, v36
	v_mul_f32_e32 v53, v53, v37
	v_mul_f32_e32 v54, v54, v38
	v_mul_f32_e32 v55, v55, v39
	v_cmp_lt_i32_e32 vcc, 0, v56
	v_cndmask_b32_e32 v40, 0, v40, vcc
	v_cmp_lt_i32_e32 vcc, 1, v56
	v_cndmask_b32_e32 v41, 0, v41, vcc
	v_cmp_lt_i32_e32 vcc, 2, v56
	v_cndmask_b32_e32 v42, 0, v42, vcc
	v_cmp_lt_i32_e32 vcc, 3, v56
	v_cndmask_b32_e32 v43, 0, v43, vcc
	v_cmp_lt_i32_e32 vcc, 4, v56
	v_cndmask_b32_e32 v44, 0, v44, vcc
	v_cmp_lt_i32_e32 vcc, 5, v56
	v_cndmask_b32_e32 v45, 0, v45, vcc
	v_cmp_lt_i32_e32 vcc, 6, v56
	v_cndmask_b32_e32 v46, 0, v46, vcc
	v_cmp_lt_i32_e32 vcc, 7, v56
	v_cndmask_b32_e32 v47, 0, v47, vcc
	v_cmp_lt_i32_e32 vcc, 8, v56
	v_cndmask_b32_e32 v48, 0, v48, vcc
	v_cmp_lt_i32_e32 vcc, 9, v56
	v_cndmask_b32_e32 v49, 0, v49, vcc
	v_cmp_lt_i32_e32 vcc, 10, v56
	v_cndmask_b32_e32 v50, 0, v50, vcc
	v_cmp_lt_i32_e32 vcc, 11, v56
	v_cndmask_b32_e32 v51, 0, v51, vcc
	v_cmp_lt_i32_e32 vcc, 12, v56
	v_cndmask_b32_e32 v52, 0, v52, vcc
	v_cmp_lt_i32_e32 vcc, 13, v56
	v_cndmask_b32_e32 v53, 0, v53, vcc
	v_cmp_lt_i32_e32 vcc, 14, v56
	v_cndmask_b32_e32 v54, 0, v54, vcc
	v_cmp_lt_i32_e32 vcc, 15, v56
	v_cndmask_b32_e32 v55, 0, v55, vcc
	ds_write_b128 v96, v[40:43]
	ds_write_b128 v96, v[44:47] offset:16
	ds_write_b128 v96, v[48:51] offset:32
	ds_write_b128 v96, v[52:55] offset:48
	v_mov_b32_e32 v4, 0
	v_mov_b32_e32 v5, 0
	s_waitcnt lgkmcnt(14)
	ds_read_b32 v2, v124
	ds_read_b32 v40, v125
	ds_read_b32 v41, v126
	ds_read_b32 v42, v127
	ds_read_b32 v43, v128
	ds_read_b32 v44, v129
	ds_read_b32 v45, v130
	ds_read_b32 v46, v131
	ds_read_b32 v47, v132
	ds_read_b32 v48, v133
	ds_read_b32 v49, v134
	ds_read_b32 v50, v135
	ds_read_b32 v51, v136
	ds_read_b32 v52, v137
	ds_read_b32 v53, v143
	ds_read_b32 v54, v145
	ds_read_b32 v55, v146
	ds_read_b32 v56, v112 offset:51456
	ds_read_b32 v57, v112 offset:51460
	ds_read_b32 v58, v112 offset:51464
	ds_read_b32 v59, v112 offset:51468
	ds_read_b32 v60, v112 offset:51472
	ds_read_b32 v61, v112 offset:51476
	ds_read_b32 v62, v112 offset:51480
	ds_read_b32 v63, v112 offset:51484
	ds_read_b32 v64, v112 offset:51488
	ds_read_b32 v65, v112 offset:51492
	ds_read_b32 v66, v112 offset:51496
	ds_read_b32 v67, v112 offset:51500
	ds_read_b32 v68, v112 offset:51504
	ds_read_b32 v69, v112 offset:51508
	ds_read_b32 v70, v112 offset:51512
	ds_read_b32 v71, v112 offset:51516
	s_waitcnt lgkmcnt(0)
	v_sub_f32_e32 v40, v2, v40
	v_sub_f32_e32 v41, v2, v41
	v_sub_f32_e32 v42, v2, v42
	v_sub_f32_e32 v43, v2, v43
	v_sub_f32_e32 v44, v2, v44
	v_sub_f32_e32 v45, v2, v45
	v_sub_f32_e32 v46, v2, v46
	v_sub_f32_e32 v47, v2, v47
	v_sub_f32_e32 v48, v2, v48
	v_sub_f32_e32 v49, v2, v49
	v_sub_f32_e32 v50, v2, v50
	v_sub_f32_e32 v51, v2, v51
	v_sub_f32_e32 v52, v2, v52
	v_sub_f32_e32 v53, v2, v53
	v_sub_f32_e32 v54, v2, v54
	v_sub_f32_e32 v55, v2, v55
	v_mul_f32_e32 v40, 0x3fb8aa3b, v40
	v_mul_f32_e32 v41, 0x3fb8aa3b, v41
	v_mul_f32_e32 v42, 0x3fb8aa3b, v42
	v_mul_f32_e32 v43, 0x3fb8aa3b, v43
	v_mul_f32_e32 v44, 0x3fb8aa3b, v44
	v_mul_f32_e32 v45, 0x3fb8aa3b, v45
	v_mul_f32_e32 v46, 0x3fb8aa3b, v46
	v_mul_f32_e32 v47, 0x3fb8aa3b, v47
	v_mul_f32_e32 v48, 0x3fb8aa3b, v48
	v_mul_f32_e32 v49, 0x3fb8aa3b, v49
	v_mul_f32_e32 v50, 0x3fb8aa3b, v50
	v_mul_f32_e32 v51, 0x3fb8aa3b, v51
	v_mul_f32_e32 v52, 0x3fb8aa3b, v52
	v_mul_f32_e32 v53, 0x3fb8aa3b, v53
	v_mul_f32_e32 v54, 0x3fb8aa3b, v54
	v_mul_f32_e32 v55, 0x3fb8aa3b, v55
	v_exp_f32_e32 v40, v40
	v_exp_f32_e32 v41, v41
	v_exp_f32_e32 v42, v42
	v_exp_f32_e32 v43, v43
	v_exp_f32_e32 v44, v44
	v_exp_f32_e32 v45, v45
	v_exp_f32_e32 v46, v46
	v_exp_f32_e32 v47, v47
	v_exp_f32_e32 v48, v48
	v_exp_f32_e32 v49, v49
	v_exp_f32_e32 v50, v50
	v_exp_f32_e32 v51, v51
	v_exp_f32_e32 v52, v52
	v_exp_f32_e32 v53, v53
	v_exp_f32_e32 v54, v54
	v_exp_f32_e32 v55, v55
	v_mul_f32_e32 v56, 0x3db504f3, v56
	v_mul_f32_e32 v57, 0x3db504f3, v57
	v_mul_f32_e32 v58, 0x3db504f3, v58
	v_mul_f32_e32 v59, 0x3db504f3, v59
	v_mul_f32_e32 v60, 0x3db504f3, v60
	v_mul_f32_e32 v61, 0x3db504f3, v61
	v_mul_f32_e32 v62, 0x3db504f3, v62
	v_mul_f32_e32 v63, 0x3db504f3, v63
	v_mul_f32_e32 v64, 0x3db504f3, v64
	v_mul_f32_e32 v65, 0x3db504f3, v65
	v_mul_f32_e32 v66, 0x3db504f3, v66
	v_mul_f32_e32 v67, 0x3db504f3, v67
	v_mul_f32_e32 v68, 0x3db504f3, v68
	v_mul_f32_e32 v69, 0x3db504f3, v69
	v_mul_f32_e32 v70, 0x3db504f3, v70
	v_mul_f32_e32 v71, 0x3db504f3, v71
	v_mul_f32_e32 v56, v56, v40
	v_mul_f32_e32 v57, v57, v41
	v_mul_f32_e32 v58, v58, v42
	v_mul_f32_e32 v59, v59, v43
	v_mul_f32_e32 v60, v60, v44
	v_mul_f32_e32 v61, v61, v45
	v_mul_f32_e32 v62, v62, v46
	v_mul_f32_e32 v63, v63, v47
	v_mul_f32_e32 v64, v64, v48
	v_mul_f32_e32 v65, v65, v49
	v_mul_f32_e32 v66, v66, v50
	v_mul_f32_e32 v67, v67, v51
	v_mul_f32_e32 v68, v68, v52
	v_mul_f32_e32 v69, v69, v53
	v_mul_f32_e32 v70, v70, v54
	v_mul_f32_e32 v71, v71, v55
	v_cndmask_b32_e64 v4, 0, v56, s[88:89]
	v_cndmask_b32_e64 v5, 0, v57, s[90:91]
	v_cndmask_b32_e64 v3, 0, v58, s[92:93]
	v_cndmask_b32_e64 v7, 0, v59, s[94:95]
	v_cndmask_b32_e64 v6, 0, v60, s[84:85]
	v_cndmask_b32_e64 v26, 0, v61, s[6:7]
	v_cndmask_b32_e64 v25, 0, v62, s[8:9]
	v_cndmask_b32_e64 v28, 0, v63, s[10:11]
	v_cndmask_b32_e64 v27, 0, v64, s[12:13]
	v_cndmask_b32_e64 v30, 0, v65, s[14:15]
	v_cndmask_b32_e64 v29, 0, v66, s[16:17]
	v_cndmask_b32_e64 v32, 0, v67, s[18:19]
	v_cndmask_b32_e64 v31, 0, v68, s[20:21]
	v_cndmask_b32_e64 v34, 0, v69, s[22:23]
	v_cndmask_b32_e64 v33, 0, v70, s[24:25]
	v_cndmask_b32_e64 v35, 0, v71, s[26:27]
; __device__ __forceinline__ unsigned pk2(float lo, float hi) { unsigned r; asm("v_cvt_pk_bf16_f32 %0, %1, %2" : "=v"(r) : "v"(lo), "v"(hi)); return r; }
; __device__ __forceinline__ void dn_prep_task(const P& p, int task, unsigned char* sm, int tid) {
;     ...
;         const int c = t2 >> 2, c_p = dir ? 63 - c : c; const float gq = gc[c_p];
;         float qv[16];
; #pragma unroll
;         for (int i = 0; i < 16; ++i) { const int s = s0 + i, s_p = dir ? 63 - s : s; qv[i] = (c_p >= s_p) ? QK[c * 65 + s] * SCALE_DK * __expf(gq - gc[s_p]) : 0.f; }
;         bf16_t* qd = (bf16_t*)(p.ws + WS_QKC) + dt * 4096 + c * 64 + s0;
;         u32x4 o0, o1; o0.x = pk2(qv[0], qv[1]); o0.y = pk2(qv[2], qv[3]); o0.z = pk2(qv[4], qv[5]); o0.w = pk2(qv[6], qv[7]);
;         o1.x = pk2(qv[8], qv[9]); o1.y = pk2(qv[10], qv[11]); o1.z = pk2(qv[12], qv[13]); o1.w = pk2(qv[14], qv[15]);
;         *(u32x4*)qd = o0; *(u32x4*)(qd + 8) = o1;
;         if (t2 < 64) { const int cc = t2, ccp = dir ? 63 - cc : cc; float* rs = (float*)(p.ws + WS_RSCS) + dt * 256;
;             rs[cc] = SCALE_DK * __expf(gc[ccp]); rs[64 + cc] = __expf(gc[63] - gc[ccp]); if (t2 == 0) rs[128] = __expf(gc[63]); }
.LBB0_639:
.LBB0_640:
.LBB0_641:
	s_or_b64 exec, exec, s[80:81]
	v_lshl_add_u64 v[36:37], s[44:45], 0, v[22:23]
	s_waitcnt lgkmcnt(0)
	v_cvt_pk_bf16_f32 v2, v4, v5
	v_cvt_pk_bf16_f32 v4, v6, v26
	v_add_co_u32_e32 v6, vcc, 0xc700000, v36
	v_cvt_pk_bf16_f32 v3, v3, v7
	v_cvt_pk_bf16_f32 v5, v25, v28
	v_cvt_pk_bf16_f32 v26, v27, v30
	v_cvt_pk_bf16_f32 v27, v29, v32
	s_nop 1
	v_addc_co_u32_e32 v7, vcc, 0, v37, vcc
	v_cvt_pk_bf16_f32 v28, v31, v34
	v_cvt_pk_bf16_f32 v29, v33, v35
	global_store_dwordx4 v[6:7], v[2:5], off
	global_store_dwordx4 v[6:7], v[26:29], off offset:16
	s_and_saveexec_b64 s[80:81], s[40:41]
	s_cbranch_execz .LBB0_644
	ds_read_b32 v6, v147
	v_readlane_b32 s72, v255, 56
	v_readlane_b32 s73, v255, 57
	s_waitcnt lgkmcnt(0)
	v_mul_f32_e32 v2, 0x3fb8aa3b, v6
	v_exp_f32_e32 v2, v2
	s_nop 0
	v_mul_f32_e32 v7, 0x3db504f3, v2
	v_lshl_add_u64 v[2:3], s[44:45], 0, v[18:19]
	v_add_co_u32_e32 v4, vcc, 0x13700000, v2
	ds_read_b32 v2, v119 offset:252
	s_nop 0
	v_addc_co_u32_e32 v5, vcc, 0, v3, vcc
	global_store_dword v[4:5], v7, off
	s_waitcnt lgkmcnt(0)
	v_sub_f32_e32 v3, v2, v6
	v_mul_f32_e32 v3, 0x3fb8aa3b, v3
	v_exp_f32_e32 v3, v3
	global_store_dword v[4:5], v3, off offset:256
	s_and_b64 exec, exec, s[72:73]
	s_cbranch_execz .LBB0_644
	v_mul_f32_e32 v2, 0x3fb8aa3b, v2
	v_exp_f32_e32 v4, v2
	v_lshl_add_u64 v[2:3], s[44:45], 0, v[20:21]
	global_store_dword v[2:3], v4, off

; __device__ __forceinline__ void scan_gload(ScanRegs& R, const P& p, int step, int b, int h, int dir, int es, int t) {
;     int task; const int m0 = scan_m0(step, b, dir, task, h); const size_t dt = (size_t)task * 2 + dir;
;     const u32x4* negw = (const u32x4*)((const bf16_t*)(p.ws + WS_NEGW) + dt * 8192);
;     const u32x4* qk = (const u32x4*)((const bf16_t*)(p.ws + WS_QKC) + dt * 4096);
;     const u32x4* knT = (const u32x4*)((const bf16_t*)(p.ws + WS_KNT) + (size_t)task * 8192);
;     const u32x4* uT = (const u32x4*)((const bf16_t*)(p.ws + WS_UT) + dt * 8192 + es * 32 * 64);
;     const u32x4* rscs = (const u32x4*)((const float*)(p.ws + WS_RSCS) + dt * 256);
;     const bf16_t* qn = (const bf16_t*)(p.ws + WS_QN) + (size_t)m0 * 512 + h * 128;
; #pragma unroll
;     for (int i = 0; i < 2; ++i) { const int pp = t + 512 * i; R.a[i] = negw[pp]; R.b[i] = *(const u32x4*)(qn + (size_t)(pp >> 4) * 512 + (pp & 15) * 8); R.d[i] = knT[pp]; }
;     R.c = qk[t];
;     R.e = uT[t & 255];
;     R.f = rscs[t < 33 ? t : 0];
; }
; __device__ __forceinline__ void scan_lwrite(unsigned char* sb, const ScanRegs& R, int t) {
; #pragma unroll
;     for (int i = 0; i < 2; ++i) { const int pp = t + 512 * i;
;         *(u32x4*)(sb + (pp >> 4) * 272 + (pp & 15) * 16) = R.a[i];
;         *(u32x4*)(sb + SC_QN + (pp >> 4) * 272 + (pp & 15) * 16) = R.b[i];
;         *(u32x4*)(sb + SC_KNT + (pp >> 3) * 144 + (pp & 7) * 16) = R.d[i]; }
;     *(u32x4*)(sb + SC_QK + (t >> 3) * 144 + (t & 7) * 16) = R.c;
;     if (t < 256) *(u32x4*)(sb + SC_UT + (t >> 3) * 144 + (t & 7) * 16) = R.e;
;     if (t < 33) *(u32x4*)(sb + SC_RS + t * 16) = R.f;
; }
; __device__ __forceinline__ void dn_scan_task(const P& p, int st, unsigned char* sm, int tid) {
;     const int combo = (st & 7) + 8 * (st >> 5), es = (st >> 3) & 3;
;     const int dir = combo & 1, h = (combo >> 1) & 3, b = combo >> 3;
;     const int wave = tid >> 6, lane = tid & 63, fr = lane & 15, g = lane >> 4;
;     bf16_t* ST = (bf16_t*)sm;
;     bf16_t* VT = ST + 32 * 136;
;     bf16_t* VS = VT + 32 * 72;
;     const int ct = wave & 3, en = wave >> 2, e0 = es * 32 + en * 16, kt0 = 2 * (wave & 3);
;     f32x4 S0 = {0.f, 0.f, 0.f, 0.f}, S1 = {0.f, 0.f, 0.f, 0.f};
;     for (int i = tid; i < 32 * 136 / 2; i += NTHREADS) ((unsigned*)ST)[i] = 0u;
;     float* O = (float*)(p.ws + (dir ? WS_KN : WS_O));
;     ScanRegs R;
.LBB0_723:
	s_or_b64 exec, exec, s[18:19]
	s_and_b64 s[18:19], s[16:17], exec
	s_mov_b32 s18, 0x13a00000
	s_cselect_b32 s18, s18, 0x11300000
	s_add_u32 s42, s2, s18
	s_addc_u32 s43, s3, 0
	s_add_i32 s19, s64, 1
	s_lshl_b32 s18, s19, 6
	s_or_b32 s19, s19, s25
	s_lshl_b32 s19, s19, 2
	s_or_b32 s20, s19, s23
	s_ashr_i32 s21, s20, 31
	s_or_b32 s18, s24, s18
	s_lshl_b64 s[30:31], s[20:21], 1
	s_or_b64 s[30:31], s[30:31], s[64:65]
	s_ashr_i32 s19, s18, 31
	s_lshl_b64 s[34:35], s[30:31], 13
	s_lshl_b64 s[20:21], s[20:21], 14
	s_lshl_b64 s[18:19], s[18:19], 10
	s_add_u32 s40, s12, s18
	s_addc_u32 s19, s13, s19
	s_lshl_b32 s18, s29, 1
	s_add_u32 s40, s40, s18
	s_addc_u32 s41, s19, 0
	v_lshl_add_u64 v[18:19], s[40:41], 0, v[0:1]
	s_lshl_b64 s[40:41], s[30:31], 14
	v_lshl_add_u64 v[10:11], v[60:61], 0, s[40:41]
	v_lshl_add_u64 v[20:21], v[62:63], 0, s[20:21]
	s_lshl_b64 s[20:21], s[30:31], 10
	v_add_co_u32_e32 v14, vcc, s63, v10
	s_add_u32 s19, s14, s40
	s_nop 0
	v_addc_co_u32_e32 v15, vcc, 0, v11, vcc
	s_addc_u32 s31, s15, s41
	s_lshl_b32 s30, s28, 1
	v_add_co_u32_e32 v22, vcc, s63, v20
	s_add_u32 s40, s19, s30
	v_lshl_add_u64 v[6:7], v[18:19], 0, v[46:47]
	v_lshl_add_u64 v[18:19], v[18:19], 0, v[48:49]
	v_addc_co_u32_e32 v23, vcc, 0, v21, vcc
	s_addc_u32 s41, s31, 0
	v_lshl_add_u64 v[28:29], v[50:51], 0, s[34:35]
	global_load_dwordx4 v[2:5], v[10:11], off
	s_nop 0
	global_load_dwordx4 v[6:9], v[6:7], off
	s_nop 0
	global_load_dwordx4 v[10:13], v[20:21], off
	s_nop 0
	global_load_dwordx4 v[14:17], v[14:15], off
	s_nop 0
	global_load_dwordx4 v[18:21], v[18:19], off
	s_nop 0
	global_load_dwordx4 v[22:25], v[22:23], off
	v_mov_b32_e32 v65, v1
	global_load_dwordx4 v[30:33], v26, s[40:41]
	v_lshl_add_u64 v[26:27], v[54:55], 0, s[20:21]
	global_load_dwordx4 v[34:37], v[28:29], off
	global_load_dwordx4 v[38:41], v[26:27], off
	s_lshl_b32 s21, s26, 11
	s_addk_i32 s21, 0xff00
	s_lshl_b32 s26, s29, 2
	v_lshl_add_u32 v26, s27, 5, v53
	s_add_u32 s26, s42, s26
	v_ashrrev_i32_e32 v27, 31, v26
	s_addc_u32 s27, s43, 0
	s_waitcnt lgkmcnt(0)
	s_barrier
	v_lshl_add_u64 v[26:27], v[26:27], 2, s[26:27]
	s_mov_b32 s19, s65
	s_mov_b32 s31, s65
	v_lshl_add_u64 v[66:67], v[26:27], 0, v[64:65]
	v_mov_b32_e32 v26, 0
	s_mov_b32 s20, 2
	v_lshl_add_u64 v[68:69], v[56:57], 0, s[18:19]
	v_lshl_add_u64 v[70:71], v[58:59], 0, s[30:31]
	s_mov_b32 s26, -2
	v_mov_b32_e32 v27, v26
	v_mov_b32_e32 v28, v26
	v_mov_b32_e32 v29, v26
	v_mov_b32_e32 v42, v26
	v_mov_b32_e32 v43, v26
	v_mov_b32_e32 v44, v26
	v_mov_b32_e32 v45, v26
	s_branch .LBB0_725
	s_nop 0
	s_nop 0
	s_nop 0
	s_nop 0
